# mixer deferred conversions: software-pipelined (next item's 8 loads in flight while the current item is converted and stored)
# speedup vs baseline: 1.0001x; 1.0001x over previous
; __device__ __forceinline__ int tid_() { int t = threadIdx.x; asm volatile("" : "+v"(t)); return t; }
; __device__ __forceinline__ void conv_table_chunk4(const float* __restrict__ src, unsigned char* __restrict__ dst, size_t base, float scale) {
;   f32x4 a[4], b[4];
; #pragma unroll
;   for (int q = 0; q < 4; ++q) {
;     size_t i = base + (size_t)q * 2048 + (size_t)tid_() * 8;
;     a[q] = *(const f32x4*)(src + i); b[q] = *(const f32x4*)(src + i + 4);
; __device__ void ph_prep(const P& p, float* lds) {
;     ...
;     } else if (it < NTR + NCV) {
;       int j = it - NTR;
;       if (j < 16) conv_chunk4(p.keys1, p_K1b, (size_t)j * 8192);
;       else if ((j -= 16) < 16) conv_chunk4(p.keys2, p_K2b, (size_t)j * 8192);
;       else if ((j -= 16) < 2048) conv_table_chunk4(p.pu, p_U8, (size_t)j * 8192, SU);
;       else if ((j -= 2048) < 2048) conv_table_chunk4(p.pv, p_V8, (size_t)j * 8192, SV);
;       else if ((j -= 2048) < 1024) conv_chunk4(p.p_p, p_Pb, (size_t)j * 8192);
;       else { j -= 1024; conv_chunk4(p.p_s, p_Pb + (size_t)TP * 256, (size_t)j * 8192); }
.LBB0_478:
	s_and_b64 vcc, exec, s[0:1]
	s_cbranch_vccnz .Lscan_go
	v_readlane_b32 s50, v228, 0
	v_readlane_b32 s51, v228, 10
	v_readlane_b32 s40, v228, 8
	v_readlane_b32 s41, v228, 9
	v_readlane_b32 s42, v228, 57
	v_readlane_b32 s43, v228, 58
	v_readlane_b32 s44, v228, 59
	v_readlane_b32 s45, v228, 60
	v_readlane_b32 s46, v228, 21
	v_readlane_b32 s47, v228, 22
	v_readlane_b32 s48, v228, 23
	v_readlane_b32 s49, v228, 24
	s_sub_u32 s50, s50, 32
	s_sub_u32 s51, s51, 32
	v_lshlrev_b32_e32 v1, 5, v220
	v_add_u32_e32 v5, 0x2000, v1
	v_add_u32_e32 v6, 0x4000, v1
	v_add_u32_e32 v7, 0x6000, v1
	v_lshlrev_b32_e32 v3, 4, v220
	v_add_u32_e32 v9, 0x1000, v3
	v_add_u32_e32 v10, 0x2000, v3
	v_add_u32_e32 v11, 0x3000, v3
	v_bfe_u32 v2, v220, 4, 3
	v_lshlrev_b32_e32 v2, 21, v2
	v_lshrrev_b32_e32 v12, 7, v220
	v_lshl_or_b32 v2, v12, 7, v2
	v_and_b32_e32 v12, 15, v220
	v_lshl_or_b32 v2, v12, 3, v2
	v_mov_b32_e32 v13, 0
	s_cmp_ge_u32 s50, 5152
	s_cbranch_scc1 .Ldef_done
	s_mov_b32 s62, 0
	s_mov_b32 s52, s50
	s_mov_b64 s[54:55], s[42:43]
	s_cmp_lt_u32 s50, 2048
	s_cbranch_scc1 .Ldq_sfirst
	s_sub_u32 s52, s50, 2048
	s_mov_b64 s[54:55], s[44:45]
	s_cmp_lt_u32 s50, 4096
	s_cbranch_scc1 .Ldq_sfirst
	s_sub_u32 s52, s50, 4096
	s_mov_b64 s[54:55], s[46:47]
	s_cmp_lt_u32 s50, 5120
	s_cbranch_scc1 .Ldq_sfirst
	s_sub_u32 s52, s50, 5120
	s_mov_b64 s[54:55], s[48:49]
.Ldq_sfirst:
	s_mov_b32 s53, 0
	s_lshl_b64 s[60:61], s[52:53], 15
	s_add_u32 s54, s54, s60
	s_addc_u32 s55, s55, s61
	global_load_dwordx4 v[16:19], v1, s[54:55]
	global_load_dwordx4 v[20:23], v1, s[54:55] offset:16
	global_load_dwordx4 v[24:27], v5, s[54:55]
	global_load_dwordx4 v[28:31], v5, s[54:55] offset:16
	global_load_dwordx4 v[32:35], v6, s[54:55]
	global_load_dwordx4 v[36:39], v6, s[54:55] offset:16
	global_load_dwordx4 v[40:43], v7, s[54:55]
	global_load_dwordx4 v[44:47], v7, s[54:55] offset:16
.Ldq_bA:
	s_add_u32 s63, s50, s51
	s_cmp_lt_u32 s63, 5152
	s_cbranch_scc0 .Ldq_lA
	s_mov_b32 s52, s63
	s_mov_b64 s[54:55], s[42:43]
	s_cmp_lt_u32 s63, 2048
	s_cbranch_scc1 .Ldq_snA
	s_sub_u32 s52, s63, 2048
	s_mov_b64 s[54:55], s[44:45]
	s_cmp_lt_u32 s63, 4096
	s_cbranch_scc1 .Ldq_snA
	s_sub_u32 s52, s63, 4096
	s_mov_b64 s[54:55], s[46:47]
	s_cmp_lt_u32 s63, 5120
	s_cbranch_scc1 .Ldq_snA
	s_sub_u32 s52, s63, 5120
	s_mov_b64 s[54:55], s[48:49]
.Ldq_snA:
	s_mov_b32 s53, 0
	s_lshl_b64 s[60:61], s[52:53], 15
	s_add_u32 s54, s54, s60
	s_addc_u32 s55, s55, s61
	global_load_dwordx4 v[56:59], v1, s[54:55]
	global_load_dwordx4 v[60:63], v1, s[54:55] offset:16
	global_load_dwordx4 v[64:67], v5, s[54:55]
	global_load_dwordx4 v[68:71], v5, s[54:55] offset:16
	global_load_dwordx4 v[72:75], v6, s[54:55]
	global_load_dwordx4 v[76:79], v6, s[54:55] offset:16
	global_load_dwordx4 v[80:83], v7, s[54:55]
	global_load_dwordx4 v[84:87], v7, s[54:55] offset:16
	s_cmp_eq_u32 s62, 0
	s_cbranch_scc1 .Ldq_fA
	s_waitcnt vmcnt(12)
	s_branch .Ldq_cA
.Ldq_fA:
	s_waitcnt vmcnt(8)
	s_branch .Ldq_cA

; __device__ __forceinline__ int tid_() { int t = threadIdx.x; asm volatile("" : "+v"(t)); return t; }
; __device__ __forceinline__ void conv_chunk4(const float* __restrict__ src, u16* __restrict__ dst, size_t base) {
;     ...
; #pragma unroll
;   for (int q = 0; q < 4; ++q) {
;     size_t i = base + (size_t)q * 2048 + (size_t)tid_() * 8;
;     BF8 t; t.u[0] = pack2(a[q][0], a[q][1]); t.u[1] = pack2(a[q][2], a[q][3]); t.u[2] = pack2(b[q][0], b[q][1]); t.u[3] = pack2(b[q][2], b[q][3]);
;     *(uint4*)(dst + i) = t.q;
;   }
; __device__ __forceinline__ void conv_table_chunk4(const float* __restrict__ src, unsigned char* __restrict__ dst, size_t base, float scale) {
;     ...
; #pragma unroll
;   for (int q = 0; q < 4; ++q) {
;     size_t i = base + (size_t)q * 2048 + (size_t)tid_() * 8;
;     int w0 = 0, w1 = 0;
;     w0 = __builtin_amdgcn_cvt_pk_fp8_f32(a[q][0] * scale, a[q][1] * scale, w0, false);
;     w0 = __builtin_amdgcn_cvt_pk_fp8_f32(a[q][2] * scale, a[q][3] * scale, w0, true);
;     w1 = __builtin_amdgcn_cvt_pk_fp8_f32(b[q][0] * scale, b[q][1] * scale, w1, false);
;     w1 = __builtin_amdgcn_cvt_pk_fp8_f32(b[q][2] * scale, b[q][3] * scale, w1, true);
;     size_t e = i >> 10; int col = (int)(i & 1023); int x = col >> 7;
;     *(uint2*)(dst + ((size_t)x * 16384 + e) * 128 + (col & 127)) = make_uint2((unsigned)w0, (unsigned)w1);
;   }
.Ldq_cA:
	s_cmp_ge_u32 s50, 4096
	s_cbranch_scc1 .Ldq_pA
	s_mov_b32 s52, s50
	s_mov_b32 s58, 0x42800000
	s_mov_b32 s59, 0xec0000
	s_cmp_lt_u32 s50, 2048
	s_cbranch_scc1 .Ldq_tA
	s_sub_u32 s52, s50, 2048
	s_mov_b32 s58, 0x41800000
	s_mov_b32 s59, 0x1ec0000
.Ldq_tA:
	s_lshl_b32 s60, s52, 10
	s_add_u32 s60, s60, s59
	s_add_u32 s56, s40, s60
	s_addc_u32 s57, s41, 0
	v_mul_f32_e32 v16, s58, v16
	v_mul_f32_e32 v17, s58, v17
	v_mul_f32_e32 v18, s58, v18
	v_mul_f32_e32 v19, s58, v19
	v_mul_f32_e32 v20, s58, v20
	v_mul_f32_e32 v21, s58, v21
	v_mul_f32_e32 v22, s58, v22
	v_mul_f32_e32 v23, s58, v23
	v_mov_b32_e32 v48, 0
	v_mov_b32_e32 v49, 0
	v_cvt_pk_fp8_f32 v48, v16, v17
	v_cvt_pk_fp8_f32 v49, v20, v21
	s_nop 0
	v_cvt_pk_fp8_f32 v48, v18, v19 op_sel:[0,0,1]
	v_cvt_pk_fp8_f32 v49, v22, v23 op_sel:[0,0,1]
	s_nop 1
	global_store_dwordx2 v2, v[48:49], s[56:57] offset:0
	v_mul_f32_e32 v24, s58, v24
	v_mul_f32_e32 v25, s58, v25
	v_mul_f32_e32 v26, s58, v26
	v_mul_f32_e32 v27, s58, v27
	v_mul_f32_e32 v28, s58, v28
	v_mul_f32_e32 v29, s58, v29
	v_mul_f32_e32 v30, s58, v30
	v_mul_f32_e32 v31, s58, v31
	v_mov_b32_e32 v50, 0
	v_mov_b32_e32 v51, 0
	v_cvt_pk_fp8_f32 v50, v24, v25
	v_cvt_pk_fp8_f32 v51, v28, v29
	s_nop 0
	v_cvt_pk_fp8_f32 v50, v26, v27 op_sel:[0,0,1]
	v_cvt_pk_fp8_f32 v51, v30, v31 op_sel:[0,0,1]
	s_nop 1
	global_store_dwordx2 v2, v[50:51], s[56:57] offset:256
	v_mul_f32_e32 v32, s58, v32
	v_mul_f32_e32 v33, s58, v33
	v_mul_f32_e32 v34, s58, v34
	v_mul_f32_e32 v35, s58, v35
	v_mul_f32_e32 v36, s58, v36
	v_mul_f32_e32 v37, s58, v37
	v_mul_f32_e32 v38, s58, v38
	v_mul_f32_e32 v39, s58, v39
	v_mov_b32_e32 v52, 0
	v_mov_b32_e32 v53, 0
	v_cvt_pk_fp8_f32 v52, v32, v33
	v_cvt_pk_fp8_f32 v53, v36, v37
	s_nop 0
	v_cvt_pk_fp8_f32 v52, v34, v35 op_sel:[0,0,1]
	v_cvt_pk_fp8_f32 v53, v38, v39 op_sel:[0,0,1]
	s_nop 1
	global_store_dwordx2 v2, v[52:53], s[56:57] offset:512
	v_mul_f32_e32 v40, s58, v40
	v_mul_f32_e32 v41, s58, v41
	v_mul_f32_e32 v42, s58, v42
	v_mul_f32_e32 v43, s58, v43
	v_mul_f32_e32 v44, s58, v44
	v_mul_f32_e32 v45, s58, v45
	v_mul_f32_e32 v46, s58, v46
	v_mul_f32_e32 v47, s58, v47
	v_mov_b32_e32 v54, 0
	v_mov_b32_e32 v55, 0
	v_cvt_pk_fp8_f32 v54, v40, v41
	v_cvt_pk_fp8_f32 v55, v44, v45
	s_nop 0
	v_cvt_pk_fp8_f32 v54, v42, v43 op_sel:[0,0,1]
	v_cvt_pk_fp8_f32 v55, v46, v47 op_sel:[0,0,1]
	s_nop 1
	global_store_dwordx2 v2, v[54:55], s[56:57] offset:768
	s_branch .Ldq_eA
.Ldq_pA:
	s_sub_u32 s52, s50, 4096
	s_mov_b32 s53, 0
	s_lshl_b64 s[60:61], s[52:53], 14
	s_add_u32 s56, s40, s60
	s_addc_u32 s57, s41, s61
	s_add_u32 s56, s56, 0x2ec0000
	s_addc_u32 s57, s57, 0
	v_cvt_pk_bf16_f32 v48, v16, v17
	v_cvt_pk_bf16_f32 v49, v18, v19
	v_cvt_pk_bf16_f32 v50, v20, v21
	v_cvt_pk_bf16_f32 v51, v22, v23
	global_store_dwordx4 v3, v[48:51], s[56:57]
	v_cvt_pk_bf16_f32 v52, v24, v25
	v_cvt_pk_bf16_f32 v53, v26, v27
	v_cvt_pk_bf16_f32 v54, v28, v29
	v_cvt_pk_bf16_f32 v55, v30, v31
	global_store_dwordx4 v9, v[52:55], s[56:57]
	v_cvt_pk_bf16_f32 v48, v32, v33
	v_cvt_pk_bf16_f32 v49, v34, v35
	v_cvt_pk_bf16_f32 v50, v36, v37
	v_cvt_pk_bf16_f32 v51, v38, v39
	global_store_dwordx4 v10, v[48:51], s[56:57]
	v_cvt_pk_bf16_f32 v52, v40, v41
	v_cvt_pk_bf16_f32 v53, v42, v43
	v_cvt_pk_bf16_f32 v54, v44, v45
	v_cvt_pk_bf16_f32 v55, v46, v47
	global_store_dwordx4 v11, v[52:55], s[56:57]
.Ldq_eA:
	s_mov_b32 s62, 1
	s_mov_b32 s50, s63
	s_cmp_ge_u32 s50, 5152
	s_cbranch_scc1 .Ldef_done

; __device__ __forceinline__ int tid_() { int t = threadIdx.x; asm volatile("" : "+v"(t)); return t; }
; __device__ __forceinline__ void conv_chunk4(const float* __restrict__ src, u16* __restrict__ dst, size_t base) {
;   f32x4 a[4], b[4];
; #pragma unroll
;   for (int q = 0; q < 4; ++q) {
;     size_t i = base + (size_t)q * 2048 + (size_t)tid_() * 8;
;     a[q] = *(const f32x4*)(src + i); b[q] = *(const f32x4*)(src + i + 4);
;   }
.Ldq_snB:
	s_mov_b32 s53, 0
	s_lshl_b64 s[60:61], s[52:53], 15
	s_add_u32 s54, s54, s60
	s_addc_u32 s55, s55, s61
	global_load_dwordx4 v[16:19], v1, s[54:55]
	global_load_dwordx4 v[20:23], v1, s[54:55] offset:16
	global_load_dwordx4 v[24:27], v5, s[54:55]
	global_load_dwordx4 v[28:31], v5, s[54:55] offset:16
	global_load_dwordx4 v[32:35], v6, s[54:55]
	global_load_dwordx4 v[36:39], v6, s[54:55] offset:16
	global_load_dwordx4 v[40:43], v7, s[54:55]
	global_load_dwordx4 v[44:47], v7, s[54:55] offset:16
	s_cmp_eq_u32 s62, 0
	s_cbranch_scc1 .Ldq_fB
	s_waitcnt vmcnt(12)
	s_branch .Ldq_cB

; __device__ __forceinline__ int tid_() { int t = threadIdx.x; asm volatile("" : "+v"(t)); return t; }
; __device__ __forceinline__ void conv_chunk4(const float* __restrict__ src, u16* __restrict__ dst, size_t base) {
;     ...
; #pragma unroll
;   for (int q = 0; q < 4; ++q) {
;     size_t i = base + (size_t)q * 2048 + (size_t)tid_() * 8;
;     BF8 t; t.u[0] = pack2(a[q][0], a[q][1]); t.u[1] = pack2(a[q][2], a[q][3]); t.u[2] = pack2(b[q][0], b[q][1]); t.u[3] = pack2(b[q][2], b[q][3]);
;     *(uint4*)(dst + i) = t.q;
;   }
; __device__ __forceinline__ void conv_table_chunk4(const float* __restrict__ src, unsigned char* __restrict__ dst, size_t base, float scale) {
;     ...
; #pragma unroll
;   for (int q = 0; q < 4; ++q) {
;     size_t i = base + (size_t)q * 2048 + (size_t)tid_() * 8;
;     int w0 = 0, w1 = 0;
;     w0 = __builtin_amdgcn_cvt_pk_fp8_f32(a[q][0] * scale, a[q][1] * scale, w0, false);
;     w0 = __builtin_amdgcn_cvt_pk_fp8_f32(a[q][2] * scale, a[q][3] * scale, w0, true);
;     w1 = __builtin_amdgcn_cvt_pk_fp8_f32(b[q][0] * scale, b[q][1] * scale, w1, false);
;     w1 = __builtin_amdgcn_cvt_pk_fp8_f32(b[q][2] * scale, b[q][3] * scale, w1, true);
;     size_t e = i >> 10; int col = (int)(i & 1023); int x = col >> 7;
;     *(uint2*)(dst + ((size_t)x * 16384 + e) * 128 + (col & 127)) = make_uint2((unsigned)w0, (unsigned)w1);
;   }
.Ldq_tB:
	s_lshl_b32 s60, s52, 10
	s_add_u32 s60, s60, s59
	s_add_u32 s56, s40, s60
	s_addc_u32 s57, s41, 0
	v_mul_f32_e32 v56, s58, v56
	v_mul_f32_e32 v57, s58, v57
	v_mul_f32_e32 v58, s58, v58
	v_mul_f32_e32 v59, s58, v59
	v_mul_f32_e32 v60, s58, v60
	v_mul_f32_e32 v61, s58, v61
	v_mul_f32_e32 v62, s58, v62
	v_mul_f32_e32 v63, s58, v63
	v_mov_b32_e32 v48, 0
	v_mov_b32_e32 v49, 0
	v_cvt_pk_fp8_f32 v48, v56, v57
	v_cvt_pk_fp8_f32 v49, v60, v61
	s_nop 0
	v_cvt_pk_fp8_f32 v48, v58, v59 op_sel:[0,0,1]
	v_cvt_pk_fp8_f32 v49, v62, v63 op_sel:[0,0,1]
	s_nop 1
	global_store_dwordx2 v2, v[48:49], s[56:57] offset:0
	v_mul_f32_e32 v64, s58, v64
	v_mul_f32_e32 v65, s58, v65
	v_mul_f32_e32 v66, s58, v66
	v_mul_f32_e32 v67, s58, v67
	v_mul_f32_e32 v68, s58, v68
	v_mul_f32_e32 v69, s58, v69
	v_mul_f32_e32 v70, s58, v70
	v_mul_f32_e32 v71, s58, v71
	v_mov_b32_e32 v50, 0
	v_mov_b32_e32 v51, 0
	v_cvt_pk_fp8_f32 v50, v64, v65
	v_cvt_pk_fp8_f32 v51, v68, v69
	s_nop 0
	v_cvt_pk_fp8_f32 v50, v66, v67 op_sel:[0,0,1]
	v_cvt_pk_fp8_f32 v51, v70, v71 op_sel:[0,0,1]
	s_nop 1
	global_store_dwordx2 v2, v[50:51], s[56:57] offset:256
	v_mul_f32_e32 v72, s58, v72
	v_mul_f32_e32 v73, s58, v73
	v_mul_f32_e32 v74, s58, v74
	v_mul_f32_e32 v75, s58, v75
	v_mul_f32_e32 v76, s58, v76
	v_mul_f32_e32 v77, s58, v77
	v_mul_f32_e32 v78, s58, v78
	v_mul_f32_e32 v79, s58, v79
	v_mov_b32_e32 v52, 0
	v_mov_b32_e32 v53, 0
	v_cvt_pk_fp8_f32 v52, v72, v73
	v_cvt_pk_fp8_f32 v53, v76, v77
	s_nop 0
	v_cvt_pk_fp8_f32 v52, v74, v75 op_sel:[0,0,1]
	v_cvt_pk_fp8_f32 v53, v78, v79 op_sel:[0,0,1]
	s_nop 1
	global_store_dwordx2 v2, v[52:53], s[56:57] offset:512
	v_mul_f32_e32 v80, s58, v80
	v_mul_f32_e32 v81, s58, v81
	v_mul_f32_e32 v82, s58, v82
	v_mul_f32_e32 v83, s58, v83
	v_mul_f32_e32 v84, s58, v84
	v_mul_f32_e32 v85, s58, v85
	v_mul_f32_e32 v86, s58, v86
	v_mul_f32_e32 v87, s58, v87
	v_mov_b32_e32 v54, 0
	v_mov_b32_e32 v55, 0
	v_cvt_pk_fp8_f32 v54, v80, v81
	v_cvt_pk_fp8_f32 v55, v84, v85
	s_nop 0
	v_cvt_pk_fp8_f32 v54, v82, v83 op_sel:[0,0,1]
	v_cvt_pk_fp8_f32 v55, v86, v87 op_sel:[0,0,1]
	s_nop 1
	global_store_dwordx2 v2, v[54:55], s[56:57] offset:768
	s_branch .Ldq_eB
.Ldq_pB:
	s_sub_u32 s52, s50, 4096
	s_mov_b32 s53, 0
	s_lshl_b64 s[60:61], s[52:53], 14
	s_add_u32 s56, s40, s60
	s_addc_u32 s57, s41, s61
	s_add_u32 s56, s56, 0x2ec0000
	s_addc_u32 s57, s57, 0
	v_cvt_pk_bf16_f32 v48, v56, v57
	v_cvt_pk_bf16_f32 v49, v58, v59
	v_cvt_pk_bf16_f32 v50, v60, v61
	v_cvt_pk_bf16_f32 v51, v62, v63
	global_store_dwordx4 v3, v[48:51], s[56:57]
	v_cvt_pk_bf16_f32 v52, v64, v65
	v_cvt_pk_bf16_f32 v53, v66, v67
	v_cvt_pk_bf16_f32 v54, v68, v69
	v_cvt_pk_bf16_f32 v55, v70, v71
	global_store_dwordx4 v9, v[52:55], s[56:57]
	v_cvt_pk_bf16_f32 v48, v72, v73
	v_cvt_pk_bf16_f32 v49, v74, v75
	v_cvt_pk_bf16_f32 v50, v76, v77
	v_cvt_pk_bf16_f32 v51, v78, v79
	global_store_dwordx4 v10, v[48:51], s[56:57]
	v_cvt_pk_bf16_f32 v52, v80, v81
	v_cvt_pk_bf16_f32 v53, v82, v83
	v_cvt_pk_bf16_f32 v54, v84, v85
	v_cvt_pk_bf16_f32 v55, v86, v87
	global_store_dwordx4 v11, v[52:55], s[56:57]
.Ldq_eB:
	s_mov_b32 s62, 1
	s_mov_b32 s50, s63
	s_cmp_ge_u32 s50, 5152
	s_cbranch_scc1 .Ldef_done
	s_branch .Ldq_bA
